# FFN weight conversion moved into the waits of grid barriers 1 and 2: non-leader workgroups arrive, every wave converts one queue item, then the deferred completion wait
# baseline (speedup 1.0000x reference)
; #define LAS __attribute__((address_space(3)))
; __device__ __forceinline__ unsigned xb_add(unsigned* p, unsigned v) { return __hip_atomic_fetch_add(p, v, __ATOMIC_RELAXED, __HIP_MEMORY_SCOPE_AGENT); }
; __device__ __forceinline__ unsigned xb_xcc_id() { return (unsigned)__builtin_amdgcn_s_getreg((3 << 11) | 20) & 0xFu; }
; __device__ __forceinline__ XcdBarrier xcd_barrier_post(unsigned* bar, volatile LAS unsigned* st) {
;     XcdBarrier b; b.bar = bar; b.x = xb_xcc_id(); b.st = st;
;     if (threadIdx.x == 0) (void)xb_add(&bar[XB_XCNT(b.x)], 1u);
;     return b;
; __global__ void __launch_bounds__(512, 2) fwd_megakernel(Params P) {
;     extern __shared__ __attribute__((aligned(16))) unsigned char lds_raw[];
;     lds_t* lds = (lds_t*)lds_raw;
;     ...
;     const int G = gridDim.x, bx = (int)blockIdx.x;
;     unsigned char* ws = P.ws;
;     volatile LAS unsigned* misc = (volatile LAS unsigned*)(lds + 131072 + 512);
;     const int wave0 = __builtin_amdgcn_readfirstlane((int)threadIdx.x >> 6);
;     if (threadIdx.x < 2) misc[threadIdx.x] = 0u;
;     __syncthreads();
;     XcdBarrier bar = xcd_barrier_post((unsigned*)(ws + WS_BAR), misc); bar.w0 = wave0;
_Z14fwd_megakernel6Params:
	s_mov_b32 s99, 0
	s_load_dwordx2 s[68:69], s[0:1], 0x70
	s_load_dwordx4 s[60:63], s[0:1], 0x60
	s_load_dwordx8 s[4:11], s[0:1], 0x40
	s_load_dword s96, s[0:1], 0x78
	v_readfirstlane_b32 s3, v0
	v_cmp_gt_u32_e32 vcc, 2, v0
	s_waitcnt lgkmcnt(0)
	v_writelane_b32 v255, s4, 0
	s_nop 1
	v_writelane_b32 v255, s5, 1
	v_writelane_b32 v255, s6, 2
	v_writelane_b32 v255, s7, 3
	v_writelane_b32 v255, s8, 4
	v_writelane_b32 v255, s9, 5
	v_writelane_b32 v255, s10, 6
	v_writelane_b32 v255, s11, 7
	s_add_u32 s4, s0, 0x78
	s_addc_u32 s5, s1, 0
	v_writelane_b32 v255, s4, 8
	s_nop 1
	v_writelane_b32 v255, s5, 9
	v_writelane_b32 v255, s3, 10
	s_and_saveexec_b64 s[4:5], vcc
	v_lshl_add_u32 v1, v0, 2, 0
	v_add_u32_e32 v1, 0x20200, v1
	v_mov_b32_e32 v2, 0
	ds_write_b32 v1, v2
	ds_write_b32 v1, v2 offset:32
	s_or_b64 exec, exec, s[4:5]
	s_add_u32 s4, s68, 0x80000
	s_addc_u32 s5, s69, 0
	s_waitcnt lgkmcnt(0)
	s_barrier
	v_writelane_b32 v255, s4, 11
	s_getreg_b32 s3, hwreg(HW_REG_XCC_ID, 0, 4)
	s_and_b32 s33, s3, 15
	v_writelane_b32 v255, s5, 12
	v_cmp_eq_u32_e32 vcc, 0, v0
	s_and_saveexec_b64 s[4:5], vcc
	s_cbranch_execz .LBB0_5
	s_mov_b64 s[6:7], exec
	v_mbcnt_lo_u32_b32 v0, s6, 0
	v_mbcnt_hi_u32_b32 v0, s7, v0
	v_cmp_eq_u32_e32 vcc, 0, v0
	s_and_b64 s[8:9], exec, vcc
	s_mov_b64 exec, s[8:9]
	s_cbranch_execz .LBB0_5
	s_bcnt1_i32_b64 s6, s[6:7]
	s_lshl_b32 s3, s33, 8
	v_mov_b32_e32 v1, s6
	v_readlane_b32 s6, v255, 11
	v_mov_b32_e32 v0, s3
	v_readlane_b32 s7, v255, 12
	s_nop 4
	global_atomic_add v0, v1, s[6:7] offset:1024
	s_and_b32 s98, s2, 7
	s_cmp_lg_u32 s98, s33
	s_cbranch_scc1 .Lxm_bad
	s_cmp_eq_u32 s96, 0x100
	s_cbranch_scc1 .Lxm_ok

; __device__ __forceinline__ unsigned xb_ld(unsigned* p)              { return __hip_atomic_load(p, __ATOMIC_RELAXED, __HIP_MEMORY_SCOPE_AGENT); }
; __device__ __forceinline__ unsigned xb_add(unsigned* p, unsigned v) { return __hip_atomic_fetch_add(p, v, __ATOMIC_RELAXED, __HIP_MEMORY_SCOPE_AGENT); }
; #define XB_SPIN(cond, bar) do { unsigned _sp = 0; while (cond) { __builtin_amdgcn_s_sleep(1); \
;     if ((++_sp & 255u) == 0u) { if (xb_ld(&(bar)[XB_TMO])) break; if (_sp > XB_SPIN_CAP) { atomicAdd(&(bar)[XB_TMO], 1u); break; } } } } while (0)
; __device__ __forceinline__ void xcd_barrier(const XcdBarrier& b) {
;     ...
;         const unsigned old = xb_add(&bar[XB_XSUB(b.x)], 1u);
;         const unsigned gen = old / nloc;
;         if (old + 1u == (gen + 1u) * nloc) {
;             __builtin_amdgcn_fence(__ATOMIC_RELEASE, "agent");
;             asm volatile("s_waitcnt vmcnt(0)" ::: "memory");
;             const unsigned og = xb_add(&bar[XB_TOP], 1u);
;             const unsigned tg = og / nx;
;             if (og + 1u == (tg + 1u) * nx) xb_add(&bar[XB_TOPGEN], 1u);
;             else XB_SPIN(xb_ld(&bar[XB_TOPGEN]) == tg, bar);
;             __builtin_amdgcn_fence(__ATOMIC_ACQUIRE, "agent");
;             xb_add(&bar[XB_XGEN(b.x)], 1u);
;             asm volatile("s_waitcnt vmcnt(0)" ::: "memory");
;         } else {
;             XB_SPIN(xb_ld(&bar[XB_XGEN(b.x)]) == gen, bar);
;             __builtin_amdgcn_fence(__ATOMIC_ACQUIRE, "agent");
.LBB0_66:
	s_or_b64 exec, exec, s[8:9]
	v_cvt_f32_u32_e32 v4, v2
	s_waitcnt vmcnt(0)
	v_readfirstlane_b32 s3, v3
	v_sub_u32_e32 v3, 0, v2
	v_rcp_iflag_f32_e32 v4, v4
	v_add_u32_e32 v5, s3, v1
	v_mul_f32_e32 v4, 0x4f7ffffe, v4
	v_cvt_u32_f32_e32 v4, v4
	v_mul_lo_u32 v1, v3, v4
	v_mul_hi_u32 v1, v4, v1
	v_add_u32_e32 v1, v4, v1
	v_mul_hi_u32 v1, v5, v1
	v_mul_lo_u32 v3, v1, v2
	v_sub_u32_e32 v3, v5, v3
	v_add_u32_e32 v4, 1, v1
	v_cmp_ge_u32_e32 vcc, v3, v2
	s_nop 1
	v_cndmask_b32_e32 v1, v1, v4, vcc
	v_sub_u32_e32 v4, v3, v2
	v_cndmask_b32_e32 v3, v3, v4, vcc
	v_add_u32_e32 v4, 1, v1
	v_cmp_ge_u32_e32 vcc, v3, v2
	v_add_u32_e32 v3, 1, v5
	s_nop 0
	v_cndmask_b32_e32 v1, v1, v4, vcc
	v_mul_lo_u32 v4, v2, v1
	v_add_u32_e32 v2, v4, v2
	v_cmp_ne_u32_e32 vcc, v3, v2
	s_and_saveexec_b64 s[6:7], vcc
	s_xor_b64 s[6:7], exec, s[6:7]
	s_cbranch_execz .LBB0_80
	s_cmp_lg_u32 s96, 0x100
	s_cbranch_scc1 .Lbf_norm_1
	v_add_u32_e32 v2, 1, v1
	v_mov_b32_e32 v0, 0x20220
	ds_write_b32 v0, v2
	s_branch .LBB0_80
.Lbf_norm_1:
	s_waitcnt lgkmcnt(0)
	buffer_inv sc1
	v_mov_b32_e32 v0, 0x2000
	global_load_dword v0, v0, s[4:5] offset:1024 sc1
	s_add_u32 s14, s4, 0x2400
	s_addc_u32 s15, s5, 0
	s_waitcnt vmcnt(0)
	v_cmp_eq_u32_e32 vcc, v0, v1
	s_and_saveexec_b64 s[8:9], vcc
	s_cbranch_execz .LBB0_79
	s_add_u32 s12, s68, 0x80200
	s_addc_u32 s13, s69, 0
	s_mov_b32 s3, 1
	s_mov_b64 s[16:17], 0
	v_mov_b32_e32 v0, 0
	s_branch .LBB0_70

; #define LAS __attribute__((address_space(3)))
; DI void p0_transpose_item(const float* W, int K, int N, bf16_t* WT, const float* gain, bool is_win, LAS float* scr, int item, int lane) {
;     const int nblk = N / 32, kb = item / nblk, nb = item % nblk, k0 = 64 * kb, n0 = 32 * nb;
;     float cs = 1.f; int prow = n0;
;     if (is_win) { prow = win_perm(n0); if (n0 < 512) cs = 0.125f; else if (n0 >= 1280 && n0 < 1792) cs = 0.08838834764831845f; }
; DI void p2_ffn_weights(const Params& P, lds_t* lds, int GP, int bx, int wave, int lane) {
;     unsigned char* ws = P.ws;
;     LAS float* scr = (LAS float*)(lds + wave * 16384);
;     constexpr int I_UP = (DM / 64) * (FF / 32), I_DN = (FF / 64) * (DM / 32);
;     for (int it = bx * 8 + wave; it < I_UP + I_DN; it += GP * 8) {
;         if (it < I_UP) p0_transpose_item(P.w_up, DM, FF, (bf16_t*)(ws + WS_WUP), P.norm2, false, scr, it, lane);
;         else p0_transpose_item(P.w_down, FF, DM, (bf16_t*)(ws + WS_WDN), nullptr, false, scr, it - I_UP, lane);
;     }
.LBB0_100:
	s_or_b64 exec, exec, s[0:1]
	s_cmpk_lt_i32 s2, 0x2ec
	v_mov_b32_e32 v8, v175
	s_cselect_b64 s[0:1], -1, 0
	s_cmpk_gt_i32 s2, 0x2eb
	s_waitcnt lgkmcnt(0)
	s_barrier
	s_cselect_b32 s98, 1, 0
	v_mov_b32_e32 v137, 0x20220
	ds_read_b32 v138, v137
	s_waitcnt lgkmcnt(0)
	s_nop 0
	v_readfirstlane_b32 s99, v138
	s_cmp_eq_u32 s99, 0
	s_cbranch_scc1 .Lbf_skip_1
	v_writelane_b32 v255, s0, 20
	v_writelane_b32 v255, s4, 21
	v_writelane_b32 v255, s5, 22
	v_writelane_b32 v255, s6, 23
	v_writelane_b32 v255, s7, 24
	v_writelane_b32 v255, s8, 25
	v_writelane_b32 v255, s9, 26
	v_writelane_b32 v255, s10, 27
	v_writelane_b32 v255, s11, 28
	v_writelane_b32 v255, s12, 29
	v_writelane_b32 v255, s13, 30
	v_writelane_b32 v255, s24, 31
	v_writelane_b32 v255, s25, 32
	v_writelane_b32 v255, s26, 33
	v_writelane_b32 v255, s27, 34
	v_writelane_b32 v255, s28, 35
	v_writelane_b32 v255, s29, 36
	v_writelane_b32 v255, s30, 37
	v_writelane_b32 v255, s31, 38
	v_and_b32_e32 v133, 7, v201
	v_lshlrev_b32_e32 v132, 4, v133
	v_lshlrev_b32_e32 v135, 2, v133
	v_lshrrev_b32_e32 v133, 3, v201
	v_lshlrev_b32_e32 v134, 5, v133
	v_lshlrev_b32_e32 v136, 4, v133
	v_mov_b32_e32 v138, 1
	v_mov_b32_e32 v139, 0
	s_lshr_b32 s27, s2, 3
	s_sub_u32 s28, s2, 0xe2
	s_cmpk_ge_u32 s2, 0xf0
	s_cselect_b32 s27, s28, s27
	s_lshl_b32 s28, s27, 8
	s_add_u32 s28, s28, 0x50100
	s_add_u32 s24, s68, s28
	s_addc_u32 s25, s69, 0
	s_mov_b64 exec, 1
	global_atomic_add v137, v139, v138, s[24:25] sc0
	s_mov_b64 exec, -1
	s_waitcnt vmcnt(0)
	v_readfirstlane_b32 s31, v137
	s_mul_i32 s26, s31, 30
	s_add_u32 s26, s26, s27
	s_cmpk_lt_u32 s26, 0x1000
	s_cbranch_scc0 .Lbf1_done
	s_cmpk_lt_u32 s26, 0x800
	s_cbranch_scc0 .Lbf1x_dn_p
	s_lshr_b32 s28, s26, 7
	s_and_b32 s29, s26, 0x7f
	v_readlane_b32 s4, v255, 4
	v_readlane_b32 s5, v255, 5
	s_lshl_b32 s30, s28, 20
	s_lshl_b32 s0, s29, 7
	s_add_u32 s30, s30, s0
	s_add_u32 s4, s4, s30
	s_addc_u32 s5, s5, 0
	s_lshl_b32 s30, s29, 16
	s_lshl_b32 s0, s28, 7
	s_add_u32 s30, s30, s0
	s_add_u32 s30, s30, 0xa00000
	s_add_u32 s6, s68, s30
	s_addc_u32 s7, s69, 0
	s_movk_i32 s8, 0x4000
	s_movk_i32 s9, 0x800
	s_mov_b32 s10, 1
	s_branch .Lbf1x_gp_p

; #define LAS __attribute__((address_space(3)))
; DI unsigned pk(float a, float b) { f32x2 v = {a, b}; bf16x2_t r = __builtin_convertvector(v, bf16x2_t); return __builtin_bit_cast(unsigned, r); }
; __device__ __forceinline__ unsigned xb_ld(unsigned* p)              { return __hip_atomic_load(p, __ATOMIC_RELAXED, __HIP_MEMORY_SCOPE_AGENT); }
; #define XB_SPIN(cond, bar) do { unsigned _sp = 0; while (cond) { __builtin_amdgcn_s_sleep(1); \
;     if ((++_sp & 255u) == 0u) { if (xb_ld(&(bar)[XB_TMO])) break; if (_sp > XB_SPIN_CAP) { atomicAdd(&(bar)[XB_TMO], 1u); break; } } } } while (0)
; __device__ __forceinline__ void xcd_barrier(const XcdBarrier& b) {
;     ...
;             XB_SPIN(xb_ld(&bar[XB_XGEN(b.x)]) == gen, bar);
;             __builtin_amdgcn_fence(__ATOMIC_ACQUIRE, "agent");
; DI void p0_transpose_item(const float* W, int K, int N, bf16_t* WT, const float* gain, bool is_win, LAS float* scr, int item, int lane) {
;     const int nblk = N / 32, kb = item / nblk, nb = item % nblk, k0 = 64 * kb, n0 = 32 * nb;
;     float cs = 1.f; int prow = n0;
;     if (is_win) { prow = win_perm(n0); if (n0 < 512) cs = 0.125f; else if (n0 >= 1280 && n0 < 1792) cs = 0.08838834764831845f; }
; #pragma unroll 8
;     for (int i = 0; i < 32; ++i) { const int kk = 2 * i + (lane >> 5); float w = __builtin_nontemporal_load(W + (size_t)(k0 + kk) * N + n0 + (lane & 31)) * cs;     if (gain) w *= gain[k0 + kk]; scr[kk * 33 + (lane & 31)] = w; }
;     asm volatile("s_waitcnt lgkmcnt(0)" ::: "memory");
;     const int c = lane & 7;
; #pragma unroll
;     for (int j = 0; j < 4; ++j) { const int n = (lane >> 3) + 8 * j; const LAS float* s = scr + (8 * c) * 33 + n;
;         u32x4 o; o.x = pk(s[0 * 33], s[1 * 33]); o.y = pk(s[2 * 33], s[3 * 33]); o.z = pk(s[4 * 33], s[5 * 33]); o.w = pk(s[6 * 33], s[7 * 33]);
;         *(u32x4*)(WT + (size_t)(prow + n) * K + k0 + 8 * c) = o; }
;     asm volatile("s_waitcnt lgkmcnt(0)" ::: "memory");
.Lbf1x_gp_p:
	v_readlane_b32 s12, v255, 2
	v_readlane_b32 s13, v255, 3
	s_lshl_b32 s28, s28, 8
	s_add_u32 s12, s12, s28
	s_addc_u32 s13, s13, 0
	s_lshl_b32 s28, s8, 3
	v_mad_u32_u24 v104, v133, s28, v132
	v_add_u32_e32 v105, s8, v104
	v_add_u32_e32 v106, s8, v105
	v_add_u32_e32 v107, s8, v106
	v_add_u32_e32 v108, s8, v107
	v_add_u32_e32 v109, s8, v108
	v_add_u32_e32 v110, s8, v109
	v_add_u32_e32 v111, s8, v110
	s_nop 3
	global_load_dwordx4 v[64:67], v104, s[4:5] nt
	global_load_dwordx4 v[68:71], v105, s[4:5] nt
	global_load_dwordx4 v[72:75], v106, s[4:5] nt
	global_load_dwordx4 v[76:79], v107, s[4:5] nt
	global_load_dwordx4 v[80:83], v108, s[4:5] nt
	global_load_dwordx4 v[84:87], v109, s[4:5] nt
	global_load_dwordx4 v[88:91], v110, s[4:5] nt
	global_load_dwordx4 v[92:95], v111, s[4:5] nt
	global_load_dwordx4 v[96:99], v134, s[12:13]
	global_load_dwordx4 v[100:103], v134, s[12:13] offset:16
	s_waitcnt vmcnt(0)
	v_mad_u32_u24 v112, v135, s9, v136
	v_add_u32_e32 v113, s9, v112
	v_add_u32_e32 v114, s9, v113
	v_add_u32_e32 v115, s9, v114
	s_cmp_eq_u32 s10, 0
	s_cbranch_scc1 .Lbf1x_nog_la
	v_mul_f32_e32 v64, v64, v96
	v_mul_f32_e32 v65, v65, v96
	v_mul_f32_e32 v66, v66, v96
	v_mul_f32_e32 v67, v67, v96
	v_mul_f32_e32 v68, v68, v97
	v_mul_f32_e32 v69, v69, v97
	v_mul_f32_e32 v70, v70, v97
	v_mul_f32_e32 v71, v71, v97
	v_mul_f32_e32 v72, v72, v98
	v_mul_f32_e32 v73, v73, v98
	v_mul_f32_e32 v74, v74, v98
	v_mul_f32_e32 v75, v75, v98
	v_mul_f32_e32 v76, v76, v99
	v_mul_f32_e32 v77, v77, v99
	v_mul_f32_e32 v78, v78, v99
	v_mul_f32_e32 v79, v79, v99
	v_mul_f32_e32 v80, v80, v100
	v_mul_f32_e32 v81, v81, v100
	v_mul_f32_e32 v82, v82, v100
	v_mul_f32_e32 v83, v83, v100
	v_mul_f32_e32 v84, v84, v101
	v_mul_f32_e32 v85, v85, v101
	v_mul_f32_e32 v86, v86, v101
	v_mul_f32_e32 v87, v87, v101
	v_mul_f32_e32 v88, v88, v102
	v_mul_f32_e32 v89, v89, v102
	v_mul_f32_e32 v90, v90, v102
	v_mul_f32_e32 v91, v91, v102
	v_mul_f32_e32 v92, v92, v103
	v_mul_f32_e32 v93, v93, v103
	v_mul_f32_e32 v94, v94, v103
	v_mul_f32_e32 v95, v95, v103
.Lbf1x_nog_la:
	v_cvt_pk_bf16_f32 v116, v64, v68
	v_cvt_pk_bf16_f32 v117, v72, v76
	v_cvt_pk_bf16_f32 v118, v80, v84
	v_cvt_pk_bf16_f32 v119, v88, v92
	global_store_dwordx4 v112, v[116:119], s[6:7]
	v_cvt_pk_bf16_f32 v120, v65, v69
	v_cvt_pk_bf16_f32 v121, v73, v77
	v_cvt_pk_bf16_f32 v122, v81, v85
	v_cvt_pk_bf16_f32 v123, v89, v93
	global_store_dwordx4 v113, v[120:123], s[6:7]
	v_cvt_pk_bf16_f32 v124, v66, v70
	v_cvt_pk_bf16_f32 v125, v74, v78
	v_cvt_pk_bf16_f32 v126, v82, v86
	v_cvt_pk_bf16_f32 v127, v90, v94
	global_store_dwordx4 v114, v[124:127], s[6:7]
	v_cvt_pk_bf16_f32 v128, v67, v71
	v_cvt_pk_bf16_f32 v129, v75, v79
	v_cvt_pk_bf16_f32 v130, v83, v87
	v_cvt_pk_bf16_f32 v131, v91, v95
	global_store_dwordx4 v115, v[128:131], s[6:7]
.Lbf1_done:
	s_waitcnt vmcnt(0)
	v_readlane_b32 s0, v255, 20
	v_readlane_b32 s4, v255, 21
	v_readlane_b32 s5, v255, 22
	v_readlane_b32 s6, v255, 23
	v_readlane_b32 s7, v255, 24
	v_readlane_b32 s8, v255, 25
	v_readlane_b32 s9, v255, 26
	v_readlane_b32 s10, v255, 27
	v_readlane_b32 s11, v255, 28
	v_readlane_b32 s12, v255, 29
	v_readlane_b32 s13, v255, 30
	v_readlane_b32 s24, v255, 31
	v_readlane_b32 s25, v255, 32
	v_readlane_b32 s26, v255, 33
	v_readlane_b32 s27, v255, 34
	v_readlane_b32 s28, v255, 35
	v_readlane_b32 s29, v255, 36
	v_readlane_b32 s30, v255, 37
	v_readlane_b32 s31, v255, 38
	v_readlane_b32 s101, v255, 13
	s_cmp_lg_u32 s101, 0
	s_cbranch_scc1 .Lbf_nw_1
	s_mov_b64 exec, 1
	s_sub_u32 s99, s99, 1
	s_lshl_b32 s101, s33, 8
	s_add_u32 s101, s101, 0x82400
	v_mov_b32_e32 v137, s101
	v_mov_b32_e32 v139, s99
	s_mov_b32 s101, 0x40000
.Lbf_poll_1:
	global_load_dword v138, v137, s[68:69] sc1
	s_waitcnt vmcnt(0)
	v_cmp_ne_u32_e32 vcc, v138, v139
	s_cbranch_vccnz .Lbf_pd_1
	s_sleep 1
	s_sub_u32 s101, s101, 1
	s_cmp_eq_u32 s101, 0
	s_cbranch_scc0 .Lbf_poll_1

; __device__ __forceinline__ unsigned xb_ld(unsigned* p)              { return __hip_atomic_load(p, __ATOMIC_RELAXED, __HIP_MEMORY_SCOPE_AGENT); }
; #define XB_SPIN(cond, bar) do { unsigned _sp = 0; while (cond) { __builtin_amdgcn_s_sleep(1); \
;     if ((++_sp & 255u) == 0u) { if (xb_ld(&(bar)[XB_TMO])) break; if (_sp > XB_SPIN_CAP) { atomicAdd(&(bar)[XB_TMO], 1u); break; } } } } while (0)
; __device__ __forceinline__ void xcd_barrier(const XcdBarrier& b) {
;     ...
;             XB_SPIN(xb_ld(&bar[XB_XGEN(b.x)]) == gen, bar);
;             __builtin_amdgcn_fence(__ATOMIC_ACQUIRE, "agent");
;             asm volatile("s_waitcnt vmcnt(0)" ::: "memory");
;         }
;     }
;     __syncthreads();
;     __host__ __device__ bool at(long L, Unit& u) const {
;         if (L >= nwg) return false;
;         int wgid = (int)L; { const int q = nwg / NXCD, r = nwg % NXCD, xcd = wgid % NXCD, off = wgid / NXCD; wgid = (xcd < r ? xcd * (q + 1) : r * (q + 1) + (xcd - r) * q) + off; }
;         const int nig = WGM * nN, gid = wgid / nig, fm = gid * WGM, gsz = (nM - fm) < WGM ? (nM - fm) : WGM;
;         u.pm = fm + ((wgid % nig) % gsz); u.pn = (wgid % nig) / gsz; u.k0 = 0; u.nt = ntk; return true;
.Lbf_nw_1:
	s_barrier
	v_readlane_b32 s101, v255, 13
	s_cmp_lg_u32 s101, 0
	s_cbranch_scc1 .Lbf_skip_1
	s_mov_b64 exec, 1
	v_mov_b32_e32 v137, 0x20220
	v_mov_b32_e32 v138, 0
	ds_write_b32 v137, v138
	s_mov_b64 exec, -1
.Lbf_skip_1:
	s_cmp_lg_u32 s98, 0
	s_load_dword s100, s[68:69], 0x53000
	s_waitcnt lgkmcnt(0)
	s_cbranch_scc1 .LBB0_106
	s_ashr_i32 s3, s2, 31
	s_lshr_b32 s3, s3, 29
	s_add_i32 s3, s2, s3
	s_and_b32 s4, s3, -8
	s_sub_i32 s6, s2, s4
	s_cmp_gt_i32 s6, 3
	s_cbranch_scc0 .LBB0_103
	s_mul_i32 s4, s6, 0x5d
	s_add_i32 s7, s4, 4
	s_cbranch_execz .LBB0_104
	s_branch .LBB0_105

; #define LAS __attribute__((address_space(3)))
; DI void p2_ffn_weights(const Params& P, lds_t* lds, int GP, int bx, int wave, int lane) {
;     unsigned char* ws = P.ws;
;     LAS float* scr = (LAS float*)(lds + wave * 16384);
;     constexpr int I_UP = (DM / 64) * (FF / 32), I_DN = (FF / 64) * (DM / 32);
;     for (int it = bx * 8 + wave; it < I_UP + I_DN; it += GP * 8) {
;         if (it < I_UP) p0_transpose_item(P.w_up, DM, FF, (bf16_t*)(ws + WS_WUP), P.norm2, false, scr, it, lane);
;         else p0_transpose_item(P.w_down, FF, DM, (bf16_t*)(ws + WS_WDN), nullptr, false, scr, it - I_UP, lane);
;     }
; __global__ void __launch_bounds__(512, 2) fwd_megakernel(Params P) {
;     ...
;     {
;       const int GP = G - NS2;
;       unsigned* flag = (unsigned*)(ws + WS_FLAG);
;       if (bx < GP) {
.LBB0_429:
	s_or_b64 exec, exec, s[0:1]
	s_cmpk_gt_i32 s96, 0x7f
	s_cselect_b64 s[78:79], -1, 0
	s_and_b64 s[0:1], s[78:79], exec
	s_cselect_b32 s49, 16, 0
	s_sub_i32 s77, s96, s49
	s_add_u32 s80, s68, 0x50000
	s_addc_u32 s81, s69, 0
	s_cmp_ge_i32 s2, s77
	s_mov_b64 s[0:1], -1
	s_waitcnt lgkmcnt(0)
	s_barrier
	s_cselect_b32 s98, 1, 0
	v_mov_b32_e32 v137, 0x20220
	ds_read_b32 v138, v137
	s_waitcnt lgkmcnt(0)
	s_nop 0
	v_readfirstlane_b32 s99, v138
	s_cmp_eq_u32 s99, 0
	s_cbranch_scc1 .Lbf_skip_2
	v_writelane_b32 v255, s0, 20
	v_writelane_b32 v255, s4, 21
	v_writelane_b32 v255, s5, 22
	v_writelane_b32 v255, s6, 23
	v_writelane_b32 v255, s7, 24
	v_writelane_b32 v255, s8, 25
	v_writelane_b32 v255, s9, 26
	v_writelane_b32 v255, s10, 27
	v_writelane_b32 v255, s11, 28
	v_writelane_b32 v255, s12, 29
	v_writelane_b32 v255, s13, 30
	v_writelane_b32 v255, s24, 31
	v_writelane_b32 v255, s25, 32
	v_writelane_b32 v255, s26, 33
	v_writelane_b32 v255, s27, 34
	v_writelane_b32 v255, s28, 35
	v_writelane_b32 v255, s29, 36
	v_writelane_b32 v255, s30, 37
	v_writelane_b32 v255, s31, 38
	v_and_b32_e32 v133, 7, v201
	v_lshlrev_b32_e32 v132, 4, v133
	v_lshlrev_b32_e32 v135, 2, v133
	v_lshrrev_b32_e32 v133, 3, v201
	v_lshlrev_b32_e32 v134, 5, v133
	v_lshlrev_b32_e32 v136, 4, v133
	v_mov_b32_e32 v138, 1
	v_mov_b32_e32 v139, 0
	s_lshr_b32 s27, s2, 3
	s_sub_u32 s28, s2, 0xe2
	s_cmpk_ge_u32 s2, 0xf0
	s_cselect_b32 s27, s28, s27
	s_lshl_b32 s28, s27, 8
	s_add_u32 s28, s28, 0x50100
	s_add_u32 s24, s68, s28
	s_addc_u32 s25, s69, 0
	s_mov_b64 exec, 1
	global_atomic_add v137, v139, v138, s[24:25] sc0
	s_mov_b64 exec, -1
	s_waitcnt vmcnt(0)
	v_readfirstlane_b32 s31, v137
	s_mul_i32 s26, s31, 30
	s_add_u32 s26, s26, s27
	s_cmpk_lt_u32 s26, 0x1000
	s_cbranch_scc0 .Lbf2_done
	s_cmpk_lt_u32 s26, 0x800
	s_cbranch_scc0 .Lbf2x_dn_p
	s_lshr_b32 s28, s26, 7
	s_and_b32 s29, s26, 0x7f
	v_readlane_b32 s4, v255, 4
	v_readlane_b32 s5, v255, 5
	s_lshl_b32 s30, s28, 20
	s_lshl_b32 s0, s29, 7
	s_add_u32 s30, s30, s0
	s_add_u32 s4, s4, s30
	s_addc_u32 s5, s5, 0
	s_lshl_b32 s30, s29, 16
	s_lshl_b32 s0, s28, 7
	s_add_u32 s30, s30, s0
	s_add_u32 s30, s30, 0xa00000
	s_add_u32 s6, s68, s30
	s_addc_u32 s7, s69, 0
	s_movk_i32 s8, 0x4000
	s_movk_i32 s9, 0x800
	s_mov_b32 s10, 1
	s_branch .Lbf2x_gp_p

; DI int lane_id() { return (int)__builtin_amdgcn_mbcnt_hi(~0u, __builtin_amdgcn_mbcnt_lo(~0u, 0u)); }
; __global__ void __launch_bounds__(512, 2) fwd_megakernel(Params P) {
;     ...
;       if (bx < GP) {
;         { FRESH_IDS; int u = bx - 32 % GP; if (u < 0) u += GP; for (; u < 32; u += GP) attn_unit(lds, P, 512 + u, tid, wave, lane); }
;         { FRESH_IDS; int u = bx - 64 % GP; if (u < 0) u += GP; for (; u < 64; u += GP) retout_sample_unit(lds, P, 1024 + u, tid, wave, lane); }
;         if (NS2 > 0) {
;             asm volatile("s_waitcnt vmcnt(0)" ::: "memory"); __syncthreads();
;             if (wave0 == 0 && lane_id() == 0) __hip_atomic_fetch_add(flag, 1u, __ATOMIC_RELAXED, __HIP_MEMORY_SCOPE_AGENT);
;         }
;         { FRESH_IDS; int f = bx - 128 % GP; if (f < 0) f += GP; retkv_loop(lds, P, 1024, 1088, f, GP, tid, wave, lane); }
;         { FRESH_IDS;
;           const int vb = (GP % 8 == 0) ? (bx % 8) * (GP / 8) + bx / 8 : bx;
;           attn_prompt_loop(lds, P, GP, vb, tid, wave, lane);
;           retkv_loop(lds, P, 0, 1024, GP - 1 - vb, GP, tid, wave, lane);
;         }
;         { FRESH_IDS; p2_ffn_weights(P, lds, GP, bx, wave, lane); }
;       } else {
;         if (wave0 == 0) {
;             unsigned sp = 0;
;             while ((unsigned)__builtin_amdgcn_readfirstlane(__hip_atomic_load(flag, __ATOMIC_RELAXED, __HIP_MEMORY_SCOPE_AGENT)) < (unsigned)GP) { __builtin_amdgcn_s_sleep(8); if (++sp > (1u << 22)) break; }
.Lbf_skip_2:
	s_cmp_lg_u32 s98, 0
	s_cbranch_scc0 .LBB0_469
	s_andn2_b64 vcc, exec, s[10:11]
	s_cbranch_vccnz .LBB0_440
	s_mov_b32 s3, 0x400001
	v_mov_b32_e32 v0, 0
	s_branch .LBB0_433
